# P8: next trip's seven loads issued right after the current trip's data is taken, one wait before the trip's first store
# baseline (speedup 1.0000x reference)
.LBB0_965:
	s_cmp_lt_i32 s44, 9
	s_cselect_b64 s[8:9], -1, 0
	s_and_b64 s[14:15], s[8:9], s[6:7]
	s_andn2_b64 vcc, exec, s[14:15]
	s_cbranch_vccnz .LBB0_976
	v_and_b32_e32 v0, 30, v198
	v_lshl_add_u32 v0, s2, 4, v0
	s_movk_i32 s3, 0x4000
	v_cmp_gt_i32_e32 vcc, s3, v0
	s_and_saveexec_b64 s[16:17], vcc
	s_cbranch_execz .LBB0_975
	v_cvt_f32_ubyte0_e32 v1, v212
	v_mul_f32_e32 v10, 0xbed49a78, v1
	s_mov_b32 s3, 0xc2fc0000
	v_mov_b32_e32 v11, 0x42800000
	v_cmp_gt_f32_e32 vcc, s3, v10
	v_mov_b32_e32 v3, 0
	v_lshlrev_b32_e32 v6, 4, v228
	v_cndmask_b32_e32 v10, 0, v11, vcc
	v_fmac_f32_e32 v10, 0xbed49a78, v1
	v_exp_f32_e32 v1, v10
	v_mov_b32_e32 v7, v3
	v_not_b32_e32 v32, 63
	v_lshl_add_u64 v[8:9], s[42:43], 0, v[6:7]
	s_mov_b64 s[6:7], 0x1d804000
	v_cndmask_b32_e32 v10, 0, v32, vcc
	v_lshl_add_u64 v[6:7], v[8:9], 0, s[6:7]
	s_mov_b64 s[6:7], 0x1e804000
	v_ldexp_f32 v33, v1, v10
	v_and_b32_e32 v1, 3, v213
	v_lshl_add_u64 v[8:9], v[8:9], 0, s[6:7]
	v_cmp_eq_u32_e64 s[6:7], 0, v1
	v_mbcnt_lo_u32_b32 v1, -1, 0
	v_mbcnt_hi_u32_b32 v1, -1, v1
	v_and_b32_e32 v10, 64, v1
	v_add_u32_e32 v10, 64, v10
	v_xor_b32_e32 v11, 32, v1
	v_cmp_lt_i32_e32 vcc, v11, v10
	s_load_dwordx2 s[18:19], s[0:1], 0x10
	s_add_u32 s8, s42, 0x9004000
	v_cndmask_b32_e32 v11, v1, v11, vcc
	v_lshlrev_b32_e32 v34, 2, v11
	v_xor_b32_e32 v11, 16, v1
	v_cmp_lt_i32_e32 vcc, v11, v10
	s_addc_u32 s9, s43, 0
	v_lshlrev_b32_e32 v2, 1, v212
	v_cndmask_b32_e32 v11, v1, v11, vcc
	v_lshlrev_b32_e32 v35, 2, v11
	v_xor_b32_e32 v11, 8, v1
	v_cmp_lt_i32_e32 vcc, v11, v10
	v_lshlrev_b32_e32 v12, 3, v228
	v_lshl_add_u64 v[4:5], s[8:9], 0, v[2:3]
	v_cndmask_b32_e32 v11, v1, v11, vcc
	v_lshlrev_b32_e32 v36, 2, v11
	v_xor_b32_e32 v11, 4, v1
	v_cmp_lt_i32_e32 vcc, v11, v10
	s_lshl_b32 s3, s46, 4
	s_mov_b64 s[20:21], 0
	v_cndmask_b32_e32 v11, v1, v11, vcc
	v_lshlrev_b32_e32 v37, 2, v11
	v_xor_b32_e32 v11, 2, v1
	v_cmp_lt_i32_e32 vcc, v11, v10
	s_movk_i32 s23, 0x1e00
	v_lshlrev_b32_e32 v12, 1, v12
	v_cndmask_b32_e32 v11, v1, v11, vcc
	v_lshlrev_b32_e32 v38, 2, v11
	v_xor_b32_e32 v11, 1, v1
	v_cmp_lt_i32_e32 vcc, v11, v10
	v_mov_b32_e32 v13, v3
	s_movk_i32 s26, 0x1000
	v_cndmask_b32_e32 v10, v1, v11, vcc
	v_lshlrev_b32_e32 v39, 2, v10
	v_and_b32_e32 v10, 63, v1
	v_cmp_ne_u32_e32 vcc, 63, v10
	s_mov_b32 s22, 0x3b000000
	s_mov_b32 s27, 0x800000
	v_addc_co_u32_e32 v11, vcc, 0, v1, vcc
	v_cmp_lt_u32_e32 vcc, 61, v10
	v_lshlrev_b32_e32 v40, 2, v11
	s_brev_b32 s28, 18
	v_cndmask_b32_e64 v11, 2, 0, vcc
	v_cmp_lt_u32_e32 vcc, 60, v10
	v_add_lshl_u32 v41, v11, v1, 2
	s_mov_b32 s29, 0xfe5163ab
	v_cndmask_b32_e64 v10, 3, 0, vcc
	v_add_lshl_u32 v42, v10, v1, 2
	v_mov_b64_e32 v[10:11], s[8:9]
	s_mov_b32 s8, 0x358637bd
	v_mov_b64_e32 v[14:15], s[8:9]
	s_mov_b32 s30, 0x3c439041
	s_mov_b32 s31, 0xdb629599
	s_mov_b32 s34, 0xf534ddc0
	s_mov_b32 s35, 0xfc2757d1
	s_mov_b32 s36, 0x4e441529
	s_mov_b32 s37, 0xa2f9836e
	s_mov_b32 s38, 0x3fc90fda
	s_mov_b32 s39, 0x3f22f983
	s_mov_b32 s52, 0xbfc90fda
	v_mov_b32_e32 v43, 0x3c0881c4
	v_mov_b32_e32 v44, 0xbab64f3b
	s_brev_b32 s53, 1
	s_movk_i32 s54, 0x1f8
	s_movk_i32 s55, 0x1200
	v_lshlrev_b32_e32 v16, 1, v2
	s_mov_b32 s56, 0x19004000
	s_movk_i32 s57, 0x3fff
	v_not_b32_e32 v45, 31
	v_mov_b32_e32 v46, 0x7fc00000
	s_waitcnt lgkmcnt(0)
	v_mov_b32_e32 v249, v0
	v_mad_i64_i32 v[244:245], vcc, v249, s23, v[10:11]
	v_lshl_add_u64 v[244:245], v[244:245], 0, v[12:13]
	v_add_co_u32_e32 v242, vcc, 0x1000, v244
	s_nop 0
	v_addc_co_u32_e32 v243, vcc, 0, v245, vcc
	global_load_dwordx4 v[230:233], v[242:243], off offset:2048
	global_load_dwordx4 v[234:237], v[244:245], off
	v_add_u32_e32 v250, 1, v249
	v_mad_i64_i32 v[244:245], vcc, v250, s23, v[10:11]
	v_lshl_add_u64 v[244:245], v[244:245], 0, v[12:13]
	v_add_co_u32_e32 v242, vcc, s26, v244
	s_nop 0
	v_addc_co_u32_e32 v243, vcc, 0, v245, vcc
	global_load_dwordx4 v[238:241], v[242:243], off offset:2048
	global_load_dwordx4 v[242:245], v[244:245], off
	v_add_u32_e32 v250, v227, v249
	v_mad_i64_i32 v[248:249], vcc, v250, s23, v[4:5]
	v_ashrrev_i32_e32 v251, 31, v250
	v_add_co_u32_e32 v248, vcc, s26, v248
	v_lshl_add_u64 v[246:247], v[250:251], 2, s[18:19]
	v_addc_co_u32_e32 v249, vcc, 0, v249, vcc
	global_load_dword v246, v[246:247], off
	global_load_ushort v247, v[248:249], off offset:3072
	global_load_ushort v248, v[248:249], off offset:3136
	s_waitcnt vmcnt(0)
	s_branch .LBB0_969

.LBB0_969:
	s_waitcnt lgkmcnt(0)
	v_mad_i64_i32 v[18:19], s[8:9], v0, s23, v[10:11]
	v_lshl_add_u64 v[18:19], v[18:19], 0, v[12:13]
	v_add_co_u32_e32 v20, vcc, 0x1000, v18
	v_ashrrev_i32_e32 v1, 31, v0
	s_nop 0
	v_addc_co_u32_e32 v21, vcc, 0, v19, vcc
	v_mov_b64_e32 v[22:23], v[230:231]
	v_mov_b64_e32 v[24:25], v[232:233]
	v_mov_b64_e32 v[48:49], v[234:235]
	v_mov_b64_e32 v[50:51], v[236:237]
	v_add_u32_e32 v20, 1, v0
	v_mad_i64_i32 v[18:19], s[8:9], v20, s23, v[10:11]
	v_lshl_add_u64 v[18:19], v[18:19], 0, v[12:13]
	v_add_co_u32_e32 v26, vcc, s26, v18
	v_ashrrev_i32_e32 v21, 31, v20
	s_nop 0
	v_addc_co_u32_e32 v27, vcc, 0, v19, vcc
	v_mov_b64_e32 v[52:53], v[238:239]
	v_mov_b64_e32 v[54:55], v[240:241]
	v_mov_b64_e32 v[56:57], v[242:243]
	v_mov_b64_e32 v[58:59], v[244:245]
	v_add_u32_e32 v18, v227, v0
	v_mad_i64_i32 v[26:27], s[8:9], v18, s23, v[4:5]
	v_ashrrev_i32_e32 v19, 31, v18
	v_add_co_u32_e32 v26, vcc, s26, v26
	s_waitcnt lgkmcnt(0)
	v_lshl_add_u64 v[28:29], v[18:19], 2, s[18:19]
	v_addc_co_u32_e32 v27, vcc, 0, v27, vcc
	v_mov_b32_e32 v92, v246
	v_mov_b32_e32 v17, v247
	v_mov_b32_e32 v47, v248
	v_lshlrev_b64 v[20:21], 10, v[20:21]
	v_add_u32_e32 v249, s3, v0
	v_min_i32_e32 v249, 0x3ffe, v249
	v_mad_i64_i32 v[244:245], vcc, v249, s23, v[10:11]
	v_lshl_add_u64 v[244:245], v[244:245], 0, v[12:13]
	v_add_co_u32_e32 v242, vcc, 0x1000, v244
	s_nop 0
	v_addc_co_u32_e32 v243, vcc, 0, v245, vcc
	global_load_dwordx4 v[230:233], v[242:243], off offset:2048
	global_load_dwordx4 v[234:237], v[244:245], off
	v_add_u32_e32 v250, 1, v249
	v_mad_i64_i32 v[244:245], vcc, v250, s23, v[10:11]
	v_lshl_add_u64 v[244:245], v[244:245], 0, v[12:13]
	v_add_co_u32_e32 v242, vcc, s26, v244
	s_nop 0
	v_addc_co_u32_e32 v243, vcc, 0, v245, vcc
	global_load_dwordx4 v[238:241], v[242:243], off offset:2048
	global_load_dwordx4 v[242:245], v[244:245], off
	v_add_u32_e32 v250, v227, v249
	v_mad_i64_i32 v[248:249], vcc, v250, s23, v[4:5]
	v_ashrrev_i32_e32 v251, 31, v250
	v_add_co_u32_e32 v248, vcc, s26, v248
	v_lshl_add_u64 v[246:247], v[250:251], 2, s[18:19]
	v_addc_co_u32_e32 v249, vcc, 0, v249, vcc
	global_load_dword v246, v[246:247], off
	global_load_ushort v247, v[248:249], off offset:3072
	global_load_ushort v248, v[248:249], off offset:3136
	v_and_b32_e32 v63, 0xffff0000, v22
	v_and_b32_e32 v65, 0xffff0000, v48
	v_lshlrev_b32_e32 v26, 16, v25
	v_and_b32_e32 v27, 0xffff0000, v25
	v_lshlrev_b32_e32 v30, 16, v24
	v_and_b32_e32 v31, 0xffff0000, v24
	v_lshlrev_b32_e32 v60, 16, v23
	v_and_b32_e32 v61, 0xffff0000, v23
	v_lshlrev_b32_e32 v62, 16, v22
	v_lshlrev_b32_e32 v22, 16, v51
	v_and_b32_e32 v23, 0xffff0000, v51
	v_lshlrev_b32_e32 v24, 16, v50
	v_and_b32_e32 v25, 0xffff0000, v50
	v_lshlrev_b32_e32 v64, 16, v48
	v_mov_b32_e32 v76, v65
	v_mov_b32_e32 v77, v63
	v_lshlrev_b32_e32 v28, 16, v49
	v_and_b32_e32 v29, 0xffff0000, v49
	v_pk_mul_f32 v[48:49], v[26:27], v[26:27]
	v_pk_mul_f32 v[50:51], v[30:31], v[30:31]
	v_pk_mul_f32 v[66:67], v[22:23], v[22:23]
	v_pk_mul_f32 v[68:69], v[24:25], v[24:25]
	v_mov_b32_e32 v74, v64
	v_mov_b32_e32 v75, v62
	v_pk_mul_f32 v[76:77], v[76:77], v[76:77]
	v_mov_b32_e32 v70, v28
	v_mov_b32_e32 v71, v60
	v_mov_b32_e32 v84, v68
	v_mov_b32_e32 v85, v50
	v_mov_b32_e32 v50, v69
	v_mov_b32_e32 v68, v66
	v_mov_b32_e32 v69, v48
	v_mov_b32_e32 v48, v67
	v_pk_fma_f32 v[66:67], v[74:75], v[74:75], v[76:77]
	v_mov_b32_e32 v72, v29
	v_mov_b32_e32 v73, v61
	v_pk_fma_f32 v[66:67], v[70:71], v[70:71], v[66:67]
	v_and_b32_e32 v83, 0xffff0000, v52
	v_pk_fma_f32 v[66:67], v[72:73], v[72:73], v[66:67]
	v_lshlrev_b32_e32 v80, 16, v54
	v_pk_add_f32 v[66:67], v[84:85], v[66:67]
	v_and_b32_e32 v81, 0xffff0000, v54
	v_pk_add_f32 v[50:51], v[50:51], v[66:67]
	v_lshlrev_b32_e32 v82, 16, v52
	v_pk_add_f32 v[50:51], v[68:69], v[50:51]
	v_and_b32_e32 v69, 0xffff0000, v56
	v_pk_add_f32 v[48:49], v[48:49], v[50:51]
	ds_bpermute_b32 v51, v34, v49
	ds_bpermute_b32 v50, v34, v48
	v_lshlrev_b32_e32 v66, 16, v58
	v_and_b32_e32 v67, 0xffff0000, v58
	v_lshlrev_b32_e32 v68, 16, v56
	v_mov_b32_e32 v88, v69
	s_waitcnt lgkmcnt(0)
	v_pk_add_f32 v[48:49], v[48:49], v[50:51]
	ds_bpermute_b32 v51, v35, v49
	ds_bpermute_b32 v50, v35, v48
	v_mov_b32_e32 v89, v83
	v_pk_mul_f32 v[70:71], v[80:81], v[80:81]
	v_pk_mul_f32 v[74:75], v[66:67], v[66:67]
	v_mov_b32_e32 v86, v68
	s_waitcnt lgkmcnt(0)
	v_pk_add_f32 v[48:49], v[48:49], v[50:51]
	ds_bpermute_b32 v51, v36, v49
	ds_bpermute_b32 v50, v36, v48
	v_mov_b32_e32 v87, v82
	v_pk_mul_f32 v[88:89], v[88:89], v[88:89]
	v_mov_b32_e32 v90, v74
	v_mov_b32_e32 v91, v70
	s_waitcnt lgkmcnt(0)
	v_pk_add_f32 v[48:49], v[48:49], v[50:51]
	ds_bpermute_b32 v51, v37, v49
	ds_bpermute_b32 v50, v37, v48
	v_mov_b32_e32 v70, v75
	v_pk_fma_f32 v[74:75], v[86:87], v[86:87], v[88:89]
	v_lshlrev_b32_e32 v54, 16, v53
	v_lshlrev_b32_e32 v58, 16, v57
	s_waitcnt lgkmcnt(0)
	v_pk_add_f32 v[48:49], v[48:49], v[50:51]
	ds_bpermute_b32 v51, v38, v49
	ds_bpermute_b32 v50, v38, v48
	v_lshlrev_b32_e32 v78, 16, v55
	v_and_b32_e32 v79, 0xffff0000, v55
	v_and_b32_e32 v55, 0xffff0000, v53
	v_lshlrev_b32_e32 v52, 16, v59
	s_waitcnt lgkmcnt(0)
	v_pk_add_f32 v[48:49], v[48:49], v[50:51]
	ds_bpermute_b32 v51, v39, v49
	ds_bpermute_b32 v50, v39, v48
	v_and_b32_e32 v53, 0xffff0000, v59
	v_and_b32_e32 v59, 0xffff0000, v57
	v_mov_b32_e32 v76, v58
	v_mov_b32_e32 v77, v54
	s_waitcnt lgkmcnt(0)
	v_pk_add_f32 v[48:49], v[48:49], v[50:51]
	v_mov_b32_e32 v84, v59
	v_pk_fma_f32 v[86:87], v[48:49], s[22:23], v[14:15] op_sel_hi:[1,0,0]
	v_mov_b32_e32 v85, v55
	v_mul_f32_e32 v2, 0x4b800000, v87
	v_cmp_gt_f32_e32 vcc, s27, v87
	v_pk_fma_f32 v[48:49], v[76:77], v[76:77], v[74:75]
	v_pk_mul_f32 v[56:57], v[78:79], v[78:79]
	v_cndmask_b32_e32 v2, v87, v2, vcc
	v_rsq_f32_e32 v2, v2
	v_pk_fma_f32 v[48:49], v[84:85], v[84:85], v[48:49]
	v_pk_mul_f32 v[72:73], v[52:53], v[52:53]
	v_pk_add_f32 v[48:49], v[90:91], v[48:49]
	v_mul_f32_e32 v50, 0x45800000, v2
	v_cndmask_b32_e32 v2, v2, v50, vcc
	v_pk_add_f32 v[48:49], v[70:71], v[48:49]
	v_mov_b32_e32 v50, v72
	v_mov_b32_e32 v51, v56
	v_pk_add_f32 v[48:49], v[50:51], v[48:49]
	v_mov_b32_e32 v56, v73
	v_pk_add_f32 v[50:51], v[56:57], v[48:49]
	ds_bpermute_b32 v57, v34, v51
	ds_bpermute_b32 v56, v34, v50
	v_pk_mul_f32 v[48:49], v[2:3], v[62:63] op_sel_hi:[0,1]
	v_pk_mul_f32 v[60:61], v[2:3], v[60:61] op_sel_hi:[0,1]
	v_cvt_pk_bf16_f32 v48, v48, v49
	v_cvt_pk_bf16_f32 v49, v60, v61
	s_waitcnt lgkmcnt(0)
	v_pk_add_f32 v[56:57], v[50:51], v[56:57]
	ds_bpermute_b32 v61, v35, v57
	ds_bpermute_b32 v60, v35, v56
	v_pk_mul_f32 v[26:27], v[2:3], v[26:27] op_sel_hi:[0,1]
	v_pk_mul_f32 v[30:31], v[2:3], v[30:31] op_sel_hi:[0,1]
	v_cvt_pk_bf16_f32 v51, v26, v27
	v_cvt_pk_bf16_f32 v50, v30, v31
	s_waitcnt lgkmcnt(0)
	v_pk_add_f32 v[26:27], v[56:57], v[60:61]
	ds_bpermute_b32 v31, v36, v27
	ds_bpermute_b32 v30, v36, v26
	v_mul_f32_e32 v2, 0x4b800000, v86
	v_cmp_gt_f32_e32 vcc, s27, v86
	s_waitcnt lgkmcnt(0)
	v_pk_add_f32 v[30:31], v[26:27], v[30:31]
	ds_bpermute_b32 v57, v37, v31
	ds_bpermute_b32 v56, v37, v30
	v_cndmask_b32_e32 v2, v86, v2, vcc
	v_rsq_f32_e32 v2, v2
	s_waitcnt lgkmcnt(0)
	v_pk_add_f32 v[30:31], v[30:31], v[56:57]
	ds_bpermute_b32 v57, v38, v31
	ds_bpermute_b32 v56, v38, v30
	v_mul_f32_e32 v26, 0x45800000, v2
	v_cndmask_b32_e32 v2, v2, v26, vcc
	v_pk_mul_f32 v[26:27], v[2:3], v[64:65] op_sel_hi:[0,1]
	v_pk_mul_f32 v[28:29], v[2:3], v[28:29] op_sel_hi:[0,1]
	v_pk_mul_f32 v[24:25], v[2:3], v[24:25] op_sel_hi:[0,1]
	v_cvt_pk_bf16_f32 v26, v26, v27
	v_cvt_pk_bf16_f32 v27, v28, v29
	v_cvt_pk_bf16_f32 v28, v24, v25
	s_waitcnt lgkmcnt(0)
	v_pk_add_f32 v[24:25], v[30:31], v[56:57]
	ds_bpermute_b32 v31, v39, v25
	ds_bpermute_b32 v30, v39, v24
	v_pk_mul_f32 v[22:23], v[2:3], v[22:23] op_sel_hi:[0,1]
	v_cvt_pk_bf16_f32 v29, v22, v23
	v_lshlrev_b64 v[22:23], 10, v[0:1]
	v_lshl_add_u64 v[56:57], v[6:7], 0, v[22:23]
	s_waitcnt lgkmcnt(0)
	v_pk_add_f32 v[24:25], v[24:25], v[30:31]
	v_lshl_add_u64 v[22:23], v[8:9], 0, v[22:23]
	v_pk_fma_f32 v[24:25], v[24:25], s[22:23], v[14:15] op_sel_hi:[1,0,0]
	s_waitcnt vmcnt(0)
	global_store_dwordx4 v[22:23], v[26:29], off sc1
	v_mul_f32_e32 v1, 0x4b800000, v25
	v_cmp_gt_f32_e32 vcc, s27, v25
	global_store_dwordx4 v[56:57], v[48:51], off sc1
	s_nop 0
	v_cndmask_b32_e32 v1, v25, v1, vcc
	v_rsq_f32_e32 v1, v1
	s_nop 0
	v_mul_f32_e32 v2, 0x45800000, v1
	v_cndmask_b32_e32 v2, v1, v2, vcc
	v_mul_f32_e32 v1, 0x4b800000, v24
	v_cmp_gt_f32_e32 vcc, s27, v24
	v_pk_mul_f32 v[22:23], v[2:3], v[82:83] op_sel_hi:[0,1]
	v_pk_mul_f32 v[26:27], v[2:3], v[54:55] op_sel_hi:[0,1]
	v_cndmask_b32_e32 v1, v24, v1, vcc
	v_rsq_f32_e32 v1, v1
	v_cvt_pk_bf16_f32 v22, v22, v23
	v_cvt_pk_bf16_f32 v23, v26, v27
	v_pk_mul_f32 v[26:27], v[2:3], v[80:81] op_sel_hi:[0,1]
	v_cvt_pk_bf16_f32 v24, v26, v27
	v_pk_mul_f32 v[26:27], v[2:3], v[78:79] op_sel_hi:[0,1]
	v_mul_f32_e32 v2, 0x45800000, v1
	v_cndmask_b32_e32 v2, v1, v2, vcc
	v_cvt_f32_i32_e32 v1, v92
	v_cvt_pk_bf16_f32 v25, v26, v27
	v_pk_mul_f32 v[26:27], v[2:3], v[68:69] op_sel_hi:[0,1]
	v_pk_mul_f32 v[28:29], v[2:3], v[58:59] op_sel_hi:[0,1]
	v_cvt_pk_bf16_f32 v26, v26, v27
	v_cvt_pk_bf16_f32 v27, v28, v29
	v_pk_mul_f32 v[28:29], v[2:3], v[66:67] op_sel_hi:[0,1]
	v_pk_mul_f32 v[30:31], v[2:3], v[52:53] op_sel_hi:[0,1]
	v_cvt_pk_bf16_f32 v28, v28, v29
	v_cvt_pk_bf16_f32 v29, v30, v31
	v_lshl_add_u64 v[30:31], v[6:7], 0, v[20:21]
	v_lshl_add_u64 v[20:21], v[8:9], 0, v[20:21]
	v_mul_f32_e32 v1, v33, v1
	global_store_dwordx4 v[20:21], v[26:29], off sc1
	v_and_b32_e32 v20, 0x7fffffff, v1
	v_cmp_nlt_f32_e64 s[8:9], |v1|, s28
	global_store_dwordx4 v[30:31], v[22:25], off sc1
	s_and_saveexec_b64 s[10:11], s[8:9]
	s_xor_b64 s[24:25], exec, s[10:11]
	s_cbranch_execz .LBB0_971
	v_lshrrev_b32_e32 v2, 23, v20
	v_add_u32_e32 v2, 0xffffff88, v2
	v_cmp_lt_u32_e32 vcc, 63, v2
	s_nop 1
	v_cndmask_b32_e32 v21, 0, v32, vcc
	v_add_u32_e32 v2, v21, v2
	v_cmp_lt_u32_e64 s[8:9], 31, v2
	s_nop 1
	v_cndmask_b32_e64 v21, 0, v45, s[8:9]
	v_add_u32_e32 v2, v21, v2
	v_cmp_lt_u32_e64 s[10:11], 31, v2
	s_nop 1
	v_cndmask_b32_e64 v21, 0, v45, s[10:11]
	v_add_u32_e32 v21, v21, v2
	v_and_b32_e32 v2, 0x7fffff, v20
	v_or_b32_e32 v50, 0x800000, v2
	v_mad_u64_u32 v[22:23], s[12:13], v50, s29, 0
	v_mov_b32_e32 v2, v23
	v_mad_u64_u32 v[24:25], s[12:13], v50, s30, v[2:3]
	v_mov_b32_e32 v2, v25
	v_mad_u64_u32 v[26:27], s[12:13], v50, s31, v[2:3]
	v_mov_b32_e32 v2, v27
	v_mad_u64_u32 v[28:29], s[12:13], v50, s34, v[2:3]
	v_mov_b32_e32 v2, v29
	v_mad_u64_u32 v[30:31], s[12:13], v50, s35, v[2:3]
	v_mov_b32_e32 v2, v31
	v_mad_u64_u32 v[48:49], s[12:13], v50, s36, v[2:3]
	v_mov_b32_e32 v2, v49
	v_mad_u64_u32 v[50:51], s[12:13], v50, s37, v[2:3]
	v_cndmask_b32_e32 v23, v48, v28, vcc
	v_cndmask_b32_e32 v2, v50, v30, vcc
	v_cndmask_b32_e32 v27, v51, v48, vcc
	v_cndmask_b32_e64 v25, v2, v23, s[8:9]
	v_cndmask_b32_e64 v2, v27, v2, s[8:9]
	v_cndmask_b32_e32 v27, v30, v26, vcc
	v_cndmask_b32_e64 v23, v23, v27, s[8:9]
	v_cndmask_b32_e64 v2, v2, v25, s[10:11]
	v_cndmask_b32_e64 v25, v25, v23, s[10:11]
	v_sub_u32_e32 v29, 32, v21
	v_alignbit_b32 v30, v2, v25, v29
	v_cmp_eq_u32_e64 s[12:13], 0, v21
	v_cndmask_b32_e32 v22, v26, v22, vcc
	s_nop 0
	v_cndmask_b32_e64 v21, v30, v2, s[12:13]
	v_cndmask_b32_e32 v2, v28, v24, vcc
	v_cndmask_b32_e64 v24, v27, v2, s[8:9]
	v_cndmask_b32_e64 v23, v23, v24, s[10:11]
	v_alignbit_b32 v27, v25, v23, v29
	v_cndmask_b32_e64 v25, v27, v25, s[12:13]
	v_bfe_u32 v30, v21, 29, 1
	v_cndmask_b32_e64 v2, v2, v22, s[8:9]
	v_alignbit_b32 v27, v21, v25, 30
	v_sub_u32_e32 v31, 0, v30
	v_cndmask_b32_e64 v2, v24, v2, s[10:11]
	v_xor_b32_e32 v27, v27, v31
	v_alignbit_b32 v22, v23, v2, v29
	v_cndmask_b32_e64 v22, v22, v23, s[12:13]
	v_ffbh_u32_e32 v24, v27
	v_alignbit_b32 v23, v25, v22, 30
	v_min_u32_e32 v24, 32, v24
	v_alignbit_b32 v2, v22, v2, 30
	v_xor_b32_e32 v23, v23, v31
	v_sub_u32_e32 v25, 31, v24
	v_xor_b32_e32 v2, v2, v31
	v_alignbit_b32 v26, v27, v23, v25
	v_alignbit_b32 v2, v23, v2, v25
	v_alignbit_b32 v22, v26, v2, 9
	v_ffbh_u32_e32 v23, v22
	v_min_u32_e32 v23, 32, v23
	v_lshrrev_b32_e32 v28, 29, v21
	v_not_b32_e32 v25, v23
	v_alignbit_b32 v2, v22, v2, v25
	v_lshlrev_b32_e32 v22, 31, v28
	v_or_b32_e32 v25, 0x33000000, v22
	v_add_lshl_u32 v23, v23, v24, 23
	v_lshrrev_b32_e32 v2, 9, v2
	v_sub_u32_e32 v23, v25, v23
	v_or_b32_e32 v22, 0.5, v22
	v_lshlrev_b32_e32 v24, 23, v24
	v_or_b32_e32 v2, v23, v2
	v_lshrrev_b32_e32 v23, 9, v26
	v_sub_u32_e32 v22, v22, v24
	v_or_b32_e32 v22, v23, v22
	v_mul_f32_e32 v23, 0x3fc90fda, v22
	v_fma_f32 v24, v22, s38, -v23
	v_fmac_f32_e32 v24, 0x33a22168, v22
	v_fmac_f32_e32 v24, 0x3fc90fda, v2
	v_lshrrev_b32_e32 v21, 30, v21
	v_add_f32_e32 v2, v23, v24
	v_add_u32_e32 v21, v30, v21
